# phase 0 converts only layer-0 QKV weights; the other 10560 weight-transpose items run in waves 1-3 inside the grid-barrier wait (640 per barrier, need-ordered, two barriers ahead of first use)
# speedup vs baseline: 1.0191x; 1.0161x over previous
; #define LAS __attribute__((address_space(3)))
; __global__ void __launch_bounds__(NWAVES * 64, 2) trunk_fwd(Args args) {
;     extern __shared__ __attribute__((aligned(16))) unsigned char lds_raw[];
;     LAS unsigned char* lds = (LAS unsigned char*)lds_raw;
;     const int Gk = gridDim.x, bx = blockIdx.x;
;     const int vcu = (Gk % 8 == 0) ? (bx % 8) * (Gk / 8) + bx / 8 : bx;
;     unsigned char* ws = args.ws;
;     float* X = args.out;
;     bf16* XB = (bf16*)(ws + WS_XB);
;     float* SS = (float*)(ws + WS_SS);
;     const float* ROPE = (const float*)(ws + WS_ROPE);
;     bf16* ACT0 = (bf16*)(ws + WS_ACT);
;     bf16* ACT1 = ACT0 + (size_t)M * DM;
;     bf16* ACT2 = ACT1 + (size_t)M * DM;
;     bf16* ACT3 = ACT2 + (size_t)M * DM;
;     ...
;     volatile LAS unsigned* MISC = (volatile LAS unsigned*)(lds + 147200);
;     if (threadIdx.x < 32) MISC[threadIdx.x] = 0u;
;     __syncthreads();
;     XcdBarrier bar; bar.bar = (unsigned*)ws; bar.x = 0; bar.st = MISC + 8;
;     if (args.ph_hi - args.ph_lo > 1) bar = xcd_barrier_post((unsigned*)ws, MISC + 8);
_Z9trunk_fwd4Args:
	s_mov_b32 s101, 0
	s_mov_b32 s32, 0
	s_load_dword s4, s[0:1], 0x88
	s_load_dwordx2 s[66:67], s[0:1], 0x80
	s_mov_b32 s64, s2
	s_add_u32 s2, s0, 0x88
	s_addc_u32 s3, s1, 0
	s_mov_b32 s90, s64
	v_writelane_b32 v253, s2, 0
	s_nop 1
	v_writelane_b32 v253, s3, 1
	s_waitcnt lgkmcnt(0)
	s_and_b32 s2, s4, 7
	v_writelane_b32 v253, s4, 2
	s_cmp_lg_u32 s2, 0
	s_cbranch_scc0 .Lmy_hop636
	s_load_dwordx16 s[48:63], s[0:1], 0x40
	v_cmp_gt_u32_e32 vcc, 32, v0
	s_and_saveexec_b64 s[4:5], vcc

; #define LAS __attribute__((address_space(3)))
; __device__ __forceinline__ void xpose_item(const float* W, int K, int N, bf16* WT, const float* gain, int cmap, LAS float* scr, int item, int lane) {
;     const int nblk = N / 64, kb = item / nblk, nb = item % nblk, k0 = 64 * kb, n0 = 64 * nb;
;     const int n4 = (lane & 15) * 4, ks = lane >> 4;
;     f32x4 w[16];
; #pragma unroll
;     for (int i = 0; i < 16; ++i) w[i] = __builtin_nontemporal_load((const f32x4*)(W + (size_t)(k0 + 4 * i + ks) * N + n0 + n4));
;     if (gain) {
; #pragma unroll
;         for (int i = 0; i < 16; ++i) w[i] = w[i] * gain[k0 + 4 * i + ks];
;     }
; #pragma unroll
;     for (int i = 0; i < 16; ++i) { LAS float* d = scr + (4 * i + ks) * XP_STRIDE + n4; d[0] = w[i][0]; d[1] = w[i][1]; d[2] = w[i][2]; d[3] = w[i][3]; }
; __device__ __forceinline__ void prologue(const Args& a, LAS unsigned char* lds, int vcu, int G, int wave, int lane, int tid) {
;     ...
;     for (int it = gw; it < NITEMS; it += NGW) {
;         int r = it;
;         if (r < 2 * I_QKV) { const int l = r / I_QKV; r -= l * I_QKV; xpose_item(a.in[4] + (size_t)l * 1024 * 3072, 1024, 3072, (bf16*)(ws + WS_WQKV) + (size_t)l * 3072 * 1024, nmix + (l ? 3 : 0) * 1024, 4, scr, r, lane); continue; } r -= 2 * I_QKV;
.LBB0_525:
	s_add_i32 s0, s70, s85
	s_lshl_b32 s12, s65, 3
	s_waitcnt vmcnt(0)
	v_and_b32_e32 v2, 63, v221
	s_cmpk_gt_i32 s0, 0x2ff
	v_lshlrev_b32_e32 v66, 2, v2
	v_lshlrev_b32_e32 v68, 3, v2
	s_cbranch_scc1 .LBB0_564
.Lmy_p0_init:
	v_and_b32_e32 v4, 63, v221
	v_and_b32_e32 v72, 56, v68
	v_readlane_b32 s2, v253, 9
	s_mul_i32 s1, s70, 0x4100
	v_and_b32_e32 v70, 60, v66
	v_lshrrev_b32_e32 v67, 4, v4
	v_lshlrev_b32_e32 v98, 1, v72
	v_readlane_b32 s3, v253, 10
	s_add_i32 s1, s1, 0
	v_lshlrev_b32_e32 v2, 2, v70
	s_waitcnt lgkmcnt(0)
	v_mul_u32_u24_e32 v3, 0x104, v67
	v_lshrrev_b32_e32 v71, 3, v4
	v_lshl_add_u64 v[74:75], s[2:3], 0, v[98:99]
	v_readlane_b32 s2, v255, 8
	v_add3_u32 v69, s1, v2, v3
	v_mul_u32_u24_e32 v3, 0x104, v72
	v_lshlrev_b32_e32 v4, 2, v71
	v_readlane_b32 s3, v255, 9
	v_add3_u32 v73, s1, v3, v4
	s_lshl_b32 s1, s70, 2
	v_lshl_add_u64 v[76:77], s[2:3], 0, v[98:99]
	v_readlane_b32 s2, v255, 29
	s_add_i32 s1, s2, s1
	v_readlane_b32 s2, v255, 30
	s_add_i32 s7, s2, s70
	s_lshl_b32 s2, s70, 6
	v_readlane_b32 s3, v253, 36
	s_add_i32 s13, s3, s2
	s_lshl_b32 s2, s70, 5
	v_readlane_b32 s3, v255, 31
	v_mov_b32_e32 v3, v99
	s_add_i32 s15, s3, s2
	s_lshl_b32 s2, s70, 4
	v_readlane_b32 s3, v255, 32
	v_or_b32_e32 v84, 8, v71
	v_or_b32_e32 v85, 16, v71
	v_or_b32_e32 v86, 24, v71
	v_or_b32_e32 v87, 40, v71
	v_or_b32_e32 v88, 48, v71
	v_or_b32_e32 v89, 56, v71
	v_or_b32_e32 v90, 32, v71
	v_bitop3_b32 v91, v71, 15, 40 bitop3:0xc8
	v_bitop3_b32 v92, v71, 23, 48 bitop3:0xc8
	v_bitop3_b32 v93, v71, 31, 56 bitop3:0xc8
	v_lshl_add_u64 v[78:79], s[52:53], 0, v[2:3]
	v_lshl_add_u64 v[80:81], s[48:49], 0, v[2:3]
	s_lshl_b32 s6, s65, 5
	s_lshl_b32 s14, s65, 9
	s_lshl_b32 s16, s65, 8
	s_add_i32 s17, s3, s2
	s_lshl_b32 s18, s65, 7
	s_cmp_eq_u32 s32, 0
	s_cbranch_scc1 .Lmy_p0_noadj
	s_add_i32 s7, s7, s19
	s_lshl_b32 s0, s19, 2
	s_add_i32 s1, s1, s0
	s_lshl_b32 s0, s19, 6
	s_add_i32 s13, s13, s0
	s_lshl_b32 s0, s19, 5
	s_add_i32 s15, s15, s0
	s_lshl_b32 s0, s19, 4
	s_add_i32 s17, s17, s0
.Lmy_p0_noadj:
	s_branch .LBB0_529
.LBB0_527:
	s_waitcnt vmcnt(15)
	ds_write2_b32 v69, v62, v63 offset1:1
	ds_write2_b32 v69, v64, v65 offset0:2 offset1:3
	v_add_u32_e32 v62, 0x410, v69
	s_waitcnt vmcnt(14)
	ds_write2_b32 v62, v50, v51 offset1:1
	v_add_u32_e32 v50, 0x418, v69
	ds_write2_b32 v50, v52, v53 offset1:1
	v_add_u32_e32 v50, 0x820, v69
	s_waitcnt vmcnt(13)
	ds_write2_b32 v50, v58, v59 offset1:1
	v_add_u32_e32 v50, 0x828, v69
	ds_write2_b32 v50, v60, v61 offset1:1
	v_add_u32_e32 v50, 0xc30, v69
	s_waitcnt vmcnt(12)
	ds_write2_b32 v50, v42, v43 offset1:1
	v_add_u32_e32 v42, 0xc38, v69
	ds_write2_b32 v42, v44, v45 offset1:1
	v_add_u32_e32 v42, 0x1040, v69
	s_waitcnt vmcnt(11)
	ds_write2_b32 v42, v54, v55 offset1:1
	v_add_u32_e32 v42, 0x1048, v69
	ds_write2_b32 v42, v56, v57 offset1:1
	v_add_u32_e32 v42, 0x1450, v69
	s_waitcnt vmcnt(10)
	ds_write2_b32 v42, v34, v35 offset1:1
	v_add_u32_e32 v34, 0x1458, v69
	ds_write2_b32 v34, v36, v37 offset1:1
	v_add_u32_e32 v34, 0x1860, v69
	s_waitcnt vmcnt(9)
	ds_write2_b32 v34, v46, v47 offset1:1
	v_add_u32_e32 v34, 0x1868, v69
	ds_write2_b32 v34, v48, v49 offset1:1
	v_add_u32_e32 v34, 0x1c70, v69
	s_waitcnt vmcnt(8)
	ds_write2_b32 v34, v26, v27 offset1:1
	v_add_u32_e32 v26, 0x1c78, v69
	ds_write2_b32 v26, v28, v29 offset1:1
	v_add_u32_e32 v26, 0x2080, v69
	s_waitcnt vmcnt(7)
	ds_write2_b32 v26, v38, v39 offset1:1
	v_add_u32_e32 v26, 0x2088, v69
	ds_write2_b32 v26, v40, v41 offset1:1
	v_add_u32_e32 v26, 0x2490, v69
	s_waitcnt vmcnt(6)
	ds_write2_b32 v26, v18, v19 offset1:1
	v_add_u32_e32 v18, 0x2498, v69
	ds_write2_b32 v18, v20, v21 offset1:1
	v_add_u32_e32 v18, 0x28a0, v69
	s_waitcnt vmcnt(5)
	ds_write2_b32 v18, v30, v31 offset1:1
	v_add_u32_e32 v18, 0x28a8, v69
	ds_write2_b32 v18, v32, v33 offset1:1
	v_add_u32_e32 v18, 0x2cb0, v69
	s_waitcnt vmcnt(4)
	ds_write2_b32 v18, v10, v11 offset1:1
	v_add_u32_e32 v10, 0x2cb8, v69
	ds_write2_b32 v10, v12, v13 offset1:1
	v_add_u32_e32 v10, 0x30c0, v69
	s_waitcnt vmcnt(3)
	ds_write2_b32 v10, v22, v23 offset1:1
	v_add_u32_e32 v10, 0x30c8, v69
	ds_write2_b32 v10, v24, v25 offset1:1
	v_add_u32_e32 v10, 0x34d0, v69
	s_waitcnt vmcnt(2)
	ds_write2_b32 v10, v6, v7 offset1:1
	v_add_u32_e32 v6, 0x34d8, v69
	ds_write2_b32 v6, v8, v9 offset1:1
	v_add_u32_e32 v6, 0x38e0, v69
	s_waitcnt vmcnt(1)
	ds_write2_b32 v6, v14, v15 offset1:1
	v_add_u32_e32 v6, 0x38e8, v69
	ds_write2_b32 v6, v16, v17 offset1:1
	v_add_u32_e32 v6, 0x3cf0, v69
	s_mul_hi_i32 s3, s2, 0x600000
	s_mul_i32 s2, s2, 0x600000
	v_readlane_b32 s5, v253, 16
	s_waitcnt vmcnt(0)
	ds_write2_b32 v6, v2, v3 offset1:1
	v_add_u32_e32 v2, 0x3cf8, v69
	s_add_u32 s5, s5, s2
	v_readlane_b32 s2, v253, 17
	ds_write2_b32 v2, v4, v5 offset1:1
	s_addc_u32 s8, s2, s3
	s_ashr_i32 s11, s10, 31
	s_waitcnt lgkmcnt(0)
	s_lshl_b64 s[2:3], s[10:11], 1
	s_add_u32 s2, s5, s2
	ds_read2_b32 v[2:3], v73 offset1:65
	s_addc_u32 s3, s8, s3
	v_lshlrev_b32_e32 v98, 1, v72
	s_waitcnt lgkmcnt(0)
	v_cvt_pk_bf16_f32 v2, v2, v3
	ds_read2_b32 v[4:5], v73 offset0:130 offset1:195
	v_add_u32_e32 v14, 0x400, v73
	v_lshl_add_u64 v[8:9], s[2:3], 0, v[98:99]
	s_lshr_b32 s2, s4, 1
	s_waitcnt lgkmcnt(0)
; #define LAS __attribute__((address_space(3)))
; #define LDS_WAIT() asm volatile("s_waitcnt lgkmcnt(0)" ::: "memory")
; __device__ __forceinline__ unsigned pk2(float lo, float hi) { return pg8::cvt_pk_bf16(lo, hi); }
; __device__ __forceinline__ void xpose_item(const float* W, int K, int N, bf16* WT, const float* gain, int cmap, LAS float* scr, int item, int lane) {
;     ...
;     for (int i = 0; i < 16; ++i) { LAS float* d = scr + (4 * i + ks) * XP_STRIDE + n4; d[0] = w[i][0]; d[1] = w[i][1]; d[2] = w[i][2]; d[3] = w[i][3]; }
;     LDS_WAIT(); asm volatile("" ::: "memory");
;     int r0 = n0;
;     if (cmap == 1) { if (n0 < 1024) r0 = 2048 + n0; else if (n0 < 2048) { const int c = n0 - 1024; r0 = (c >> 7) * 256 + (c & 127); } else { const int c = n0 - 2048; r0 = (c >> 7) * 256 + 128 + (c & 127); } }
;     const int c = lane & 7;
; #pragma unroll
;     for (int j = 0; j < 8; ++j) { const int n = (lane >> 3) + 8 * j; const LAS float* sp = scr + (8 * c) * XP_STRIDE + n;
;         v4u o; o.x = pk2(sp[0 * XP_STRIDE], sp[1 * XP_STRIDE]); o.y = pk2(sp[2 * XP_STRIDE], sp[3 * XP_STRIDE]); o.z = pk2(sp[4 * XP_STRIDE], sp[5 * XP_STRIDE]); o.w = pk2(sp[6 * XP_STRIDE], sp[7 * XP_STRIDE]);
;         int rr = r0 + n;
;         if (cmap == 4) { const int cc = rr & 255; rr = (rr & ~255) + 128 * ((cc >> 5) & 1) + 32 * (cc >> 6) + (cc & 31); }
;         *(v4u*)(WT + (size_t)rr * K + k0 + 8 * c) = o; }
;     LDS_WAIT(); asm volatile("" ::: "memory");
; }
; __device__ __forceinline__ void prologue(const Args& a, LAS unsigned char* lds, int vcu, int G, int wave, int lane, int tid) {
;     ...
;     for (int it = gw; it < NITEMS; it += NGW) {
	v_cvt_pk_bf16_f32 v3, v4, v5
	ds_read2_b32 v[4:5], v14 offset0:4 offset1:69
	s_and_b32 s2, s2, 0x60
	s_and_b32 s3, s4, 0xffffff00
	s_waitcnt lgkmcnt(0)
	v_cvt_pk_bf16_f32 v4, v4, v5
	ds_read2_b32 v[6:7], v14 offset0:134 offset1:199
	s_or_b32 s3, s2, s3
	s_waitcnt lgkmcnt(0)
	v_cvt_pk_bf16_f32 v5, v6, v7
	v_or_b32_e32 v6, s3, v71
	v_ashrrev_i32_e32 v7, 31, v6
	v_lshlrev_b64 v[12:13], 11, v[6:7]
	v_lshl_add_u64 v[12:13], v[8:9], 0, v[12:13]
	ds_read2_b32 v[10:11], v73 offset0:8 offset1:73
	global_store_dwordx4 v[12:13], v[2:5], off sc1
	v_or_b32_e32 v6, 0x80, v6
	v_ashrrev_i32_e32 v7, 31, v6
	s_waitcnt lgkmcnt(0)
	v_cvt_pk_bf16_f32 v2, v10, v11
	ds_read2_b32 v[4:5], v73 offset0:138 offset1:203
	s_waitcnt lgkmcnt(0)
	v_cvt_pk_bf16_f32 v3, v4, v5
	ds_read2_b32 v[4:5], v14 offset0:12 offset1:77
	s_waitcnt lgkmcnt(0)
	v_cvt_pk_bf16_f32 v4, v4, v5
	ds_read2_b32 v[10:11], v14 offset0:142 offset1:207
	s_waitcnt lgkmcnt(0)
	v_cvt_pk_bf16_f32 v5, v10, v11
	v_or_b32_e32 v10, s3, v84
	v_ashrrev_i32_e32 v11, 31, v10
	v_lshlrev_b64 v[10:11], 11, v[10:11]
	v_lshl_add_u64 v[10:11], v[8:9], 0, v[10:11]
	ds_read2_b32 v[12:13], v73 offset0:16 offset1:81
	global_store_dwordx4 v[10:11], v[2:5], off sc1
	v_lshlrev_b64 v[6:7], 11, v[6:7]
	v_lshl_add_u64 v[6:7], v[8:9], 0, v[6:7]
	s_waitcnt lgkmcnt(0)
	v_cvt_pk_bf16_f32 v2, v12, v13
	ds_read2_b32 v[4:5], v73 offset0:146 offset1:211
	s_waitcnt lgkmcnt(0)
	v_cvt_pk_bf16_f32 v3, v4, v5
	ds_read2_b32 v[4:5], v14 offset0:20 offset1:85
	s_waitcnt lgkmcnt(0)
	v_cvt_pk_bf16_f32 v4, v4, v5
	ds_read2_b32 v[10:11], v14 offset0:150 offset1:215
	s_waitcnt lgkmcnt(0)
	v_cvt_pk_bf16_f32 v5, v10, v11
	v_or_b32_e32 v10, s3, v85
	v_ashrrev_i32_e32 v11, 31, v10
	v_lshlrev_b64 v[10:11], 11, v[10:11]
	v_lshl_add_u64 v[10:11], v[8:9], 0, v[10:11]
	ds_read2_b32 v[12:13], v73 offset0:24 offset1:89
	global_store_dwordx4 v[10:11], v[2:5], off sc1
	s_waitcnt lgkmcnt(0)
	s_nop 0
	v_cvt_pk_bf16_f32 v2, v12, v13
	ds_read2_b32 v[4:5], v73 offset0:154 offset1:219
	s_waitcnt lgkmcnt(0)
	v_cvt_pk_bf16_f32 v3, v4, v5
	ds_read2_b32 v[4:5], v14 offset0:28 offset1:93
	s_waitcnt lgkmcnt(0)
	v_cvt_pk_bf16_f32 v4, v4, v5
	ds_read2_b32 v[10:11], v14 offset0:158 offset1:223
	s_waitcnt lgkmcnt(0)
	v_cvt_pk_bf16_f32 v5, v10, v11
	v_or_b32_e32 v10, s3, v86
	v_ashrrev_i32_e32 v11, 31, v10
	v_lshlrev_b64 v[10:11], 11, v[10:11]
	v_lshl_add_u64 v[10:11], v[8:9], 0, v[10:11]
	ds_read2_b32 v[12:13], v73 offset0:32 offset1:97
	global_store_dwordx4 v[10:11], v[2:5], off sc1
	s_waitcnt lgkmcnt(0)
	s_nop 0
	v_cvt_pk_bf16_f32 v2, v12, v13
	ds_read2_b32 v[4:5], v73 offset0:162 offset1:227
	s_waitcnt lgkmcnt(0)
	v_cvt_pk_bf16_f32 v3, v4, v5
	ds_read2_b32 v[4:5], v14 offset0:36 offset1:101
	s_waitcnt lgkmcnt(0)
	v_cvt_pk_bf16_f32 v4, v4, v5
	ds_read2_b32 v[10:11], v14 offset0:166 offset1:231
	s_waitcnt lgkmcnt(0)
	v_cvt_pk_bf16_f32 v5, v10, v11
	ds_read2_b32 v[10:11], v73 offset0:40 offset1:105
	global_store_dwordx4 v[6:7], v[2:5], off sc1
	s_waitcnt lgkmcnt(0)
	s_nop 0
	v_cvt_pk_bf16_f32 v2, v10, v11
	ds_read2_b32 v[4:5], v73 offset0:170 offset1:235
	s_waitcnt lgkmcnt(0)
	v_cvt_pk_bf16_f32 v3, v4, v5
	ds_read2_b32 v[4:5], v14 offset0:44 offset1:109
	s_waitcnt lgkmcnt(0)
	v_cvt_pk_bf16_f32 v4, v4, v5
	ds_read2_b32 v[6:7], v14 offset0:174 offset1:239
	s_waitcnt lgkmcnt(0)
	v_cvt_pk_bf16_f32 v5, v6, v7
	v_mov_b32_e32 v6, 0xffffff0f
	v_bitop3_b32 v6, s4, v6, v87 bitop3:0xc8
	v_or_b32_e32 v6, s2, v6
	v_or_b32_e32 v6, 0x80, v6
	v_ashrrev_i32_e32 v7, 31, v6
	v_lshlrev_b64 v[6:7], 11, v[6:7]
	v_lshl_add_u64 v[6:7], v[8:9], 0, v[6:7]
	ds_read2_b32 v[10:11], v73 offset0:48 offset1:113
	global_store_dwordx4 v[6:7], v[2:5], off sc1
	s_waitcnt lgkmcnt(0)
	s_nop 0
	v_cvt_pk_bf16_f32 v2, v10, v11
	ds_read2_b32 v[4:5], v73 offset0:178 offset1:243
	s_waitcnt lgkmcnt(0)
	v_cvt_pk_bf16_f32 v3, v4, v5
	ds_read2_b32 v[4:5], v14 offset0:52 offset1:117
	s_waitcnt lgkmcnt(0)
	v_cvt_pk_bf16_f32 v4, v4, v5
	ds_read2_b32 v[6:7], v14 offset0:182 offset1:247
	s_waitcnt lgkmcnt(0)
	v_cvt_pk_bf16_f32 v5, v6, v7
	v_mov_b32_e32 v6, 0xffffff17
	v_bitop3_b32 v6, s4, v6, v88 bitop3:0xc8
	v_or_b32_e32 v6, s2, v6
	v_or_b32_e32 v6, 0x80, v6
	v_ashrrev_i32_e32 v7, 31, v6
	v_lshlrev_b64 v[6:7], 11, v[6:7]
	v_lshl_add_u64 v[6:7], v[8:9], 0, v[6:7]
	ds_read2_b32 v[10:11], v73 offset0:56 offset1:121
	global_store_dwordx4 v[6:7], v[2:5], off sc1
	s_waitcnt lgkmcnt(0)
	s_nop 0
	v_cvt_pk_bf16_f32 v2, v10, v11
	ds_read2_b32 v[4:5], v73 offset0:186 offset1:251
	s_waitcnt lgkmcnt(0)
	v_cvt_pk_bf16_f32 v3, v4, v5
	ds_read2_b32 v[4:5], v14 offset0:60 offset1:125
	s_waitcnt lgkmcnt(0)
	v_cvt_pk_bf16_f32 v4, v4, v5
	ds_read2_b32 v[6:7], v14 offset0:190 offset1:255
	s_waitcnt lgkmcnt(0)
	v_cvt_pk_bf16_f32 v5, v6, v7
	v_mov_b32_e32 v6, 0xffffff1f
	v_bitop3_b32 v6, s4, v6, v89 bitop3:0xc8
	v_or_b32_e32 v6, s2, v6
	v_or_b32_e32 v6, 0x80, v6
	v_ashrrev_i32_e32 v7, 31, v6
	v_lshlrev_b64 v[6:7], 11, v[6:7]
	v_lshl_add_u64 v[6:7], v[8:9], 0, v[6:7]
	global_store_dwordx4 v[6:7], v[2:5], off sc1
	s_waitcnt lgkmcnt(0)
.LBB0_528:
	s_cmp_lg_u32 s32, 0
	s_cbranch_scc1 .Lmy_p0_ret
	s_add_i32 s7, s7, s12
	s_add_i32 s1, s1, s6
	s_add_i32 s13, s13, s14
	s_add_i32 s15, s15, s16
	s_add_i32 s2, s7, 0x1c40
	s_add_i32 s17, s17, s18
	s_cmpk_gt_i32 s2, 0x2ff
	s_cbranch_scc1 .LBB0_564

; #define LAS __attribute__((address_space(3)))
; __device__ __forceinline__ void prologue(const Args& a, LAS unsigned char* lds, int vcu, int G, int wave, int lane, int tid) {
;     unsigned char* ws = a.ws;
;     LAS float* scr = (LAS float*)(lds + wave * XP_WAVE_BYTES);
;     const int gw = vcu * NWAVES + wave, NGW = G * NWAVES;
;     constexpr int I_QKV = 16 * 48, I_SQ = 16 * 16, I_POOL = 4 * 4, I_UP = 16 * 64, I_DN = 64 * 16;
;     constexpr int NITEMS = 2 * I_QKV + 2 * I_SQ + 4 * I_POOL + I_QKV + I_SQ + 4 * I_UP + 4 * I_DN;
;     const float* nmix = a.in[2]; const float* nmlp = a.in[3];
;     for (int it = gw; it < NITEMS; it += NGW) {
;         int r = it;
;         if (r < 2 * I_QKV) { const int l = r / I_QKV; r -= l * I_QKV; xpose_item(a.in[4] + (size_t)l * 1024 * 3072, 1024, 3072, (bf16*)(ws + WS_WQKV) + (size_t)l * 3072 * 1024, nmix + (l ? 3 : 0) * 1024, 4, scr, r, lane); continue; } r -= 2 * I_QKV;
;         if (r < 2 * I_SQ) { const int l = r / I_SQ; r -= l * I_SQ; xpose_item(a.in[5] + (size_t)l * 1024 * 1024, 1024, 1024, (bf16*)(ws + WS_WO) + (size_t)l * 1024 * 1024, nullptr, 4, scr, r, lane); continue; } r -= 2 * I_SQ;
;         if (r < 4 * I_POOL) { const int g = r / I_POOL; r -= g * I_POOL; xpose_item(a.in[6] + (size_t)g * 65536, 256, 256, (bf16*)(ws + WS_WPOOL) + (size_t)g * 65536, nullptr, 4, scr, r, lane); continue; } r -= 4 * I_POOL;
;         if (r < I_QKV) { xpose_item(a.in[8], 1024, 3072, (bf16*)(ws + WS_WCI), nmix + 2 * 1024, 1, scr, r, lane); continue; } r -= I_QKV;
;         if (r < I_SQ) { xpose_item(a.in[10], 1024, 1024, (bf16*)(ws + WS_WCO), nullptr, 4, scr, r, lane); continue; } r -= I_SQ;
;         if (r < 4 * I_UP) { const int l = r / I_UP; r -= l * I_UP; xpose_item(a.in[11] + (size_t)l * 1024 * 4096, 1024, 4096, (bf16*)(ws + WS_WUP) + (size_t)l * 4096 * 1024, nmlp + l * 1024, 4, scr, r, lane); continue; } r -= 4 * I_UP;
;         { const int l = r / I_DN; r -= l * I_DN; xpose_item(a.in[12] + (size_t)l * 4096 * 1024, 4096, 1024, (bf16*)(ws + WS_WDN) + (size_t)l * 1024 * 4096, nullptr, 4, scr, r, lane); }
;     }
.Lmy_items:
	s_mov_b64 exec, -1
	v_readfirstlane_b32 s3, v0
	s_lshr_b32 s3, s3, 6
	s_cmp_gt_u32 s3, 3
	s_cbranch_scc1 .LBB0_633
	v_writelane_b32 v200, s0, 0
	v_writelane_b32 v200, s1, 1
	v_writelane_b32 v200, s2, 2
	v_writelane_b32 v200, s3, 3
	v_writelane_b32 v200, s4, 4
	v_writelane_b32 v200, s5, 5
	v_writelane_b32 v200, s6, 6
	v_writelane_b32 v200, s7, 7
	v_writelane_b32 v200, s8, 8
	v_writelane_b32 v200, s9, 9
	v_writelane_b32 v200, s10, 10
	v_writelane_b32 v200, s11, 11
	v_writelane_b32 v200, s12, 12
	v_writelane_b32 v200, s13, 13
	v_writelane_b32 v200, s14, 14
	v_writelane_b32 v200, s15, 15
	v_writelane_b32 v200, s16, 16
	v_writelane_b32 v200, s17, 17
	v_writelane_b32 v200, s18, 18
	v_writelane_b32 v200, s19, 19
	v_writelane_b32 v200, s68, 20
	v_writelane_b32 v200, s69, 21
	v_writelane_b32 v200, s70, 22
	v_writelane_b32 v200, s71, 23
	v_writelane_b32 v200, s72, 24
	v_writelane_b32 v200, s73, 25
	v_writelane_b32 v200, s74, 26
	v_writelane_b32 v200, s75, 27
	v_writelane_b32 v200, s76, 28
	v_writelane_b32 v200, s77, 29
	v_writelane_b32 v200, s78, 30
	v_writelane_b32 v200, s79, 31
	v_writelane_b32 v200, s80, 32
	v_writelane_b32 v200, s81, 33
	v_writelane_b32 v200, s82, 34
	v_writelane_b32 v200, s83, 35
	v_writelane_b32 v200, s86, 36
	s_add_i32 s2, s66, -1
	s_add_i32 s4, s66, -2
	s_cmp_gt_u32 s66, 8
	s_cselect_b32 s2, s4, s2
	s_add_i32 s5, s3, -1
	s_lshl_b32 s5, s5, 8
	v_readlane_b32 s6, v255, 47
	s_lshr_b32 s7, s6, 3
	s_add_i32 s5, s5, s7
	s_cmp_ge_u32 s5, 640
	s_cbranch_scc1 .Lmy_items_restore
	s_mul_i32 s2, s2, 640
	s_add_i32 s2, s2, s5
	s_cmp_ge_u32 s2, 10560
	s_cbranch_scc1 .Lmy_items_restore
	s_mov_b32 s4, 1536
	s_cmp_ge_u32 s2, 256
	s_cselect_b32 s4, 2880, s4
	s_cmp_ge_u32 s2, 1280
	s_cselect_b32 s4, 5952, s4
	s_cmp_ge_u32 s2, 2304
	s_cselect_b32 s4, -256, s4
	s_cmp_ge_u32 s2, 2368
	s_cselect_b32 s4, 1792, s4
	s_cmp_ge_u32 s2, 3392
	s_cselect_b32 s4, 4864, s4
	s_cmp_ge_u32 s2, 4416
	s_cselect_b32 s4, -2304, s4
	s_cmp_ge_u32 s2, 5184
	s_cselect_b32 s4, -2304, s4
	s_cmp_ge_u32 s2, 5440
	s_cselect_b32 s4, -256, s4
	s_cmp_ge_u32 s2, 6464
	s_cselect_b32 s4, 2816, s4
	s_cmp_ge_u32 s2, 7488
	s_cselect_b32 s4, -6720, s4
	s_cmp_ge_u32 s2, 8256
	s_cselect_b32 s4, -6464, s4
	s_cmp_ge_u32 s2, 8512
	s_cselect_b32 s4, -2304, s4
	s_cmp_ge_u32 s2, 9536
	s_cselect_b32 s4, 768, s4
	s_add_i32 s19, s2, s4
	v_mov_b32_e32 v221, v0
	v_readlane_b32 s65, v253, 2
	s_mov_b32 s70, s3
	s_mov_b32 s85, s6
	v_readlane_b32 s28, v255, 48
	s_add_i32 s0, s70, s85
	s_sub_i32 s19, s19, s0
	s_lshl_b32 s12, s65, 3
	v_and_b32_e32 v2, 63, v221
	v_lshlrev_b32_e32 v66, 2, v2
	v_lshlrev_b32_e32 v68, 3, v2
	s_mov_b32 s32, 1
	s_branch .Lmy_p0_init
.Lmy_p0_ret:
	s_mov_b32 s32, 0
.Lmy_items_restore:
	v_readlane_b32 s0, v200, 0
	v_readlane_b32 s1, v200, 1
	v_readlane_b32 s2, v200, 2
	v_readlane_b32 s3, v200, 3
	v_readlane_b32 s4, v200, 4
	v_readlane_b32 s5, v200, 5
	v_readlane_b32 s6, v200, 6
	v_readlane_b32 s7, v200, 7
	v_readlane_b32 s8, v200, 8
	v_readlane_b32 s9, v200, 9
	v_readlane_b32 s10, v200, 10
	v_readlane_b32 s11, v200, 11
	v_readlane_b32 s12, v200, 12
	v_readlane_b32 s13, v200, 13
	v_readlane_b32 s14, v200, 14
	v_readlane_b32 s15, v200, 15
	v_readlane_b32 s16, v200, 16
	v_readlane_b32 s17, v200, 17
	v_readlane_b32 s18, v200, 18
	v_readlane_b32 s19, v200, 19
	v_readlane_b32 s68, v200, 20
	v_readlane_b32 s69, v200, 21
	v_readlane_b32 s70, v200, 22
	v_readlane_b32 s71, v200, 23
	v_readlane_b32 s72, v200, 24
	v_readlane_b32 s73, v200, 25
	v_readlane_b32 s74, v200, 26
	v_readlane_b32 s75, v200, 27
	v_readlane_b32 s76, v200, 28
	v_readlane_b32 s77, v200, 29
	v_readlane_b32 s78, v200, 30
	v_readlane_b32 s79, v200, 31
	v_readlane_b32 s80, v200, 32
	v_readlane_b32 s81, v200, 33
	v_readlane_b32 s82, v200, 34
	v_readlane_b32 s83, v200, 35
	v_readlane_b32 s86, v200, 36
	s_branch .LBB0_633
